# v15 + gate_phase j-loop: all 21 loads of an iteration issued up front (renamed destinations) and waited once instead of six serialized vmcnt(0) round trips
# speedup vs baseline: 1.0105x; 1.0048x over previous
.LBB0_205:
	s_movk_i32 s0, 0xd000
	v_add_co_u32_e64 v80, s[38:39], s0, v76
	s_movk_i32 s0, 0xe000
	s_nop 0
	v_addc_co_u32_e64 v81, s[38:39], -1, v77, s[38:39]
	v_add_co_u32_e64 v84, s[38:39], s0, v76
	s_movk_i32 s0, 0xf000
	s_nop 0
	v_addc_co_u32_e64 v85, s[38:39], -1, v77, s[38:39]
	v_add_co_u32_e64 v98, s[38:39], s0, v76
	global_load_dwordx2 v[80:81], v[80:81], off
	s_nop 0
	v_addc_co_u32_e64 v99, s[38:39], -1, v77, s[38:39]
	global_load_dwordx2 v[84:85], v[84:85], off
	v_lshl_add_u64 v[156:157], v[6:7], 0, s[46:47]
	global_load_dwordx2 v[98:99], v[98:99], off
	s_add_u32 s46, s46, 0x4000
	global_load_dwordx4 v[160:163], v[74:75], off
	s_mov_b64 s[0:1], 0x200
	s_addc_u32 s47, s47, 0
	s_cmp_eq_u32 s46, 0x20000
	global_load_dwordx2 v[164:165], v[76:77], off
	global_load_dwordx4 v[166:169], v[156:157], off
	global_load_dwordx4 v[170:173], v[156:157], off offset:16
	global_load_dwordx4 v[102:105], v[156:157], off offset:32
	global_load_dwordx4 v[106:109], v[156:157], off offset:48
	global_load_dwordx4 v[110:113], v[156:157], off offset:64
	global_load_dwordx4 v[114:117], v[156:157], off offset:80
	global_load_dwordx4 v[118:121], v[156:157], off offset:96
	global_load_dwordx4 v[122:125], v[156:157], off offset:112
	global_load_dwordx4 v[130:133], v[156:157], off offset:128
	global_load_dwordx4 v[134:137], v[156:157], off offset:144
	global_load_dwordx4 v[138:141], v[156:157], off offset:160
	global_load_dwordx4 v[142:145], v[156:157], off offset:176
	global_load_dwordx4 v[146:149], v[156:157], off offset:192
	global_load_dwordx4 v[174:177], v[156:157], off offset:208
	global_load_dwordx4 v[178:181], v[156:157], off offset:224
	global_load_dwordx4 v[182:185], v[156:157], off offset:240
	s_waitcnt vmcnt(0) lgkmcnt(0)
	v_lshlrev_b32_e32 v86, 16, v84
	v_and_b32_e32 v87, 0xffff0000, v84
	v_lshlrev_b32_e32 v100, 16, v98
	v_and_b32_e32 v101, 0xffff0000, v98
	v_lshlrev_b32_e32 v98, 16, v99
	v_and_b32_e32 v99, 0xffff0000, v99
	v_pk_mul_f32 v[126:127], v[162:163], v[98:99]
	v_lshlrev_b32_e32 v82, 16, v80
	v_and_b32_e32 v83, 0xffff0000, v80
	v_lshlrev_b32_e32 v80, 16, v81
	v_and_b32_e32 v81, 0xffff0000, v81
	v_lshlrev_b32_e32 v84, 16, v85
	v_and_b32_e32 v85, 0xffff0000, v85
	v_pk_mul_f32 v[150:151], v[160:161], v[100:101]
	v_pk_mul_f32 v[80:81], v[162:163], v[80:81]
	v_pk_mul_f32 v[82:83], v[160:161], v[82:83]
	v_pk_mul_f32 v[84:85], v[162:163], v[84:85]
	v_pk_mul_f32 v[86:87], v[160:161], v[86:87]
	v_lshl_add_u64 v[76:77], v[76:77], 0, s[0:1]
	s_mov_b64 s[0:1], 0x400
	v_lshl_add_u64 v[74:75], v[74:75], 0, s[0:1]
	s_waitcnt vmcnt(0) lgkmcnt(0)
	v_lshlrev_b32_e32 v100, 16, v164
	v_and_b32_e32 v101, 0xffff0000, v164
	v_lshlrev_b32_e32 v98, 16, v165
	v_and_b32_e32 v99, 0xffff0000, v165
	v_pk_mul_f32 v[152:153], v[162:163], v[98:99]
	v_pk_mul_f32 v[154:155], v[160:161], v[100:101]
	s_waitcnt vmcnt(0) lgkmcnt(0)
	v_pk_fma_f32 v[78:79], v[166:167], v[82:83], v[78:79] op_sel_hi:[1,0,1]
	v_pk_fma_f32 v[72:73], v[168:169], v[82:83], v[72:73] op_sel_hi:[1,0,1]
	v_pk_fma_f32 v[58:59], v[166:167], v[86:87], v[58:59] op_sel_hi:[1,0,1]
	v_pk_fma_f32 v[56:57], v[168:169], v[86:87], v[56:57] op_sel_hi:[1,0,1]
	v_pk_fma_f32 v[42:43], v[166:167], v[150:151], v[42:43] op_sel_hi:[1,0,1]
	v_pk_fma_f32 v[40:41], v[168:169], v[150:151], v[40:41] op_sel_hi:[1,0,1]
	v_pk_fma_f32 v[26:27], v[166:167], v[154:155], v[26:27] op_sel_hi:[1,0,1]
	v_pk_fma_f32 v[24:25], v[168:169], v[154:155], v[24:25] op_sel_hi:[1,0,1]
	v_pk_fma_f32 v[70:71], v[170:171], v[82:83], v[70:71] op_sel_hi:[1,0,1]
	v_pk_fma_f32 v[68:69], v[172:173], v[82:83], v[68:69] op_sel_hi:[1,0,1]
	v_pk_fma_f32 v[54:55], v[170:171], v[86:87], v[54:55] op_sel_hi:[1,0,1]
	v_pk_fma_f32 v[52:53], v[172:173], v[86:87], v[52:53] op_sel_hi:[1,0,1]
	v_pk_fma_f32 v[38:39], v[170:171], v[150:151], v[38:39] op_sel_hi:[1,0,1]
	v_pk_fma_f32 v[36:37], v[172:173], v[150:151], v[36:37] op_sel_hi:[1,0,1]
	v_pk_fma_f32 v[22:23], v[170:171], v[154:155], v[22:23] op_sel_hi:[1,0,1]
	v_pk_fma_f32 v[20:21], v[172:173], v[154:155], v[20:21] op_sel_hi:[1,0,1]
	v_pk_fma_f32 v[70:71], v[82:83], v[114:115], v[70:71] op_sel:[1,0,0]
	v_pk_fma_f32 v[68:69], v[82:83], v[116:117], v[68:69] op_sel:[1,0,0]
	v_pk_fma_f32 v[54:55], v[114:115], v[86:87], v[54:55] op_sel:[0,1,0]
	v_pk_fma_f32 v[52:53], v[116:117], v[86:87], v[52:53] op_sel:[0,1,0]
	v_pk_fma_f32 v[38:39], v[114:115], v[150:151], v[38:39] op_sel:[0,1,0]
	v_pk_fma_f32 v[36:37], v[116:117], v[150:151], v[36:37] op_sel:[0,1,0]
	v_pk_fma_f32 v[22:23], v[114:115], v[154:155], v[22:23] op_sel:[0,1,0]
	v_pk_fma_f32 v[20:21], v[116:117], v[154:155], v[20:21] op_sel:[0,1,0]
	v_pk_fma_f32 v[70:71], v[80:81], v[134:135], v[70:71] op_sel_hi:[0,1,1]
	v_pk_fma_f32 v[68:69], v[80:81], v[136:137], v[68:69] op_sel_hi:[0,1,1]
	v_pk_fma_f32 v[54:55], v[84:85], v[134:135], v[54:55] op_sel_hi:[0,1,1]
	v_pk_fma_f32 v[52:53], v[84:85], v[136:137], v[52:53] op_sel_hi:[0,1,1]
	v_pk_fma_f32 v[38:39], v[126:127], v[134:135], v[38:39] op_sel_hi:[0,1,1]
	v_pk_fma_f32 v[36:37], v[126:127], v[136:137], v[36:37] op_sel_hi:[0,1,1]
	v_pk_fma_f32 v[22:23], v[152:153], v[134:135], v[22:23] op_sel_hi:[0,1,1]
	v_pk_fma_f32 v[20:21], v[152:153], v[136:137], v[20:21] op_sel_hi:[0,1,1]
	v_pk_fma_f32 v[66:67], v[102:103], v[82:83], v[66:67] op_sel_hi:[1,0,1]
	v_pk_fma_f32 v[64:65], v[104:105], v[82:83], v[64:65] op_sel_hi:[1,0,1]
	v_pk_fma_f32 v[50:51], v[102:103], v[86:87], v[50:51] op_sel_hi:[1,0,1]
	v_pk_fma_f32 v[48:49], v[104:105], v[86:87], v[48:49] op_sel_hi:[1,0,1]
	v_pk_fma_f32 v[34:35], v[102:103], v[150:151], v[34:35] op_sel_hi:[1,0,1]
	v_pk_fma_f32 v[32:33], v[104:105], v[150:151], v[32:33] op_sel_hi:[1,0,1]
	v_pk_fma_f32 v[18:19], v[102:103], v[154:155], v[18:19] op_sel_hi:[1,0,1]
	v_pk_fma_f32 v[12:13], v[104:105], v[154:155], v[12:13] op_sel_hi:[1,0,1]
	v_pk_fma_f32 v[66:67], v[82:83], v[118:119], v[66:67] op_sel:[1,0,0]
	v_pk_fma_f32 v[64:65], v[82:83], v[120:121], v[64:65] op_sel:[1,0,0]
	v_pk_fma_f32 v[50:51], v[86:87], v[118:119], v[50:51] op_sel:[1,0,0]
	v_pk_fma_f32 v[48:49], v[86:87], v[120:121], v[48:49] op_sel:[1,0,0]
	v_pk_fma_f32 v[34:35], v[118:119], v[150:151], v[34:35] op_sel:[0,1,0]
	v_pk_fma_f32 v[32:33], v[120:121], v[150:151], v[32:33] op_sel:[0,1,0]
	v_pk_fma_f32 v[18:19], v[118:119], v[154:155], v[18:19] op_sel:[0,1,0]
	v_pk_fma_f32 v[12:13], v[120:121], v[154:155], v[12:13] op_sel:[0,1,0]
	v_pk_fma_f32 v[66:67], v[80:81], v[138:139], v[66:67] op_sel_hi:[0,1,1]
	v_pk_fma_f32 v[64:65], v[80:81], v[140:141], v[64:65] op_sel_hi:[0,1,1]
	v_pk_fma_f32 v[50:51], v[84:85], v[138:139], v[50:51] op_sel_hi:[0,1,1]
	v_pk_fma_f32 v[48:49], v[84:85], v[140:141], v[48:49] op_sel_hi:[0,1,1]
	v_pk_fma_f32 v[34:35], v[126:127], v[138:139], v[34:35] op_sel_hi:[0,1,1]
	v_pk_fma_f32 v[32:33], v[126:127], v[140:141], v[32:33] op_sel_hi:[0,1,1]
	v_pk_fma_f32 v[18:19], v[152:153], v[138:139], v[18:19] op_sel_hi:[0,1,1]
	v_pk_fma_f32 v[12:13], v[152:153], v[140:141], v[12:13] op_sel_hi:[0,1,1]
	v_pk_fma_f32 v[62:63], v[106:107], v[82:83], v[62:63] op_sel_hi:[1,0,1]
	v_pk_fma_f32 v[60:61], v[108:109], v[82:83], v[60:61] op_sel_hi:[1,0,1]
	v_pk_fma_f32 v[46:47], v[106:107], v[86:87], v[46:47] op_sel_hi:[1,0,1]
	v_pk_fma_f32 v[44:45], v[108:109], v[86:87], v[44:45] op_sel_hi:[1,0,1]
	v_pk_fma_f32 v[30:31], v[106:107], v[150:151], v[30:31] op_sel_hi:[1,0,1]
	v_pk_fma_f32 v[28:29], v[108:109], v[150:151], v[28:29] op_sel_hi:[1,0,1]
	v_pk_fma_f32 v[16:17], v[106:107], v[154:155], v[16:17] op_sel_hi:[1,0,1]
	v_pk_fma_f32 v[14:15], v[108:109], v[154:155], v[14:15] op_sel_hi:[1,0,1]
	v_pk_fma_f32 v[78:79], v[110:111], v[82:83], v[78:79] op_sel:[0,1,0]
	v_pk_fma_f32 v[72:73], v[112:113], v[82:83], v[72:73] op_sel:[0,1,0]
	v_pk_fma_f32 v[58:59], v[110:111], v[86:87], v[58:59] op_sel:[0,1,0]
	v_pk_fma_f32 v[56:57], v[112:113], v[86:87], v[56:57] op_sel:[0,1,0]
	v_pk_fma_f32 v[42:43], v[110:111], v[150:151], v[42:43] op_sel:[0,1,0]
	v_pk_fma_f32 v[40:41], v[112:113], v[150:151], v[40:41] op_sel:[0,1,0]
	v_pk_fma_f32 v[26:27], v[110:111], v[154:155], v[26:27] op_sel:[0,1,0]
	v_pk_fma_f32 v[24:25], v[112:113], v[154:155], v[24:25] op_sel:[0,1,0]
	v_pk_fma_f32 v[62:63], v[82:83], v[122:123], v[62:63] op_sel:[1,0,0]
	v_pk_fma_f32 v[60:61], v[82:83], v[124:125], v[60:61] op_sel:[1,0,0]
	v_pk_fma_f32 v[46:47], v[86:87], v[122:123], v[46:47] op_sel:[1,0,0]
	v_pk_fma_f32 v[44:45], v[86:87], v[124:125], v[44:45] op_sel:[1,0,0]
	v_pk_fma_f32 v[30:31], v[150:151], v[122:123], v[30:31] op_sel:[1,0,0]
	v_pk_fma_f32 v[28:29], v[150:151], v[124:125], v[28:29] op_sel:[1,0,0]
	v_pk_fma_f32 v[16:17], v[122:123], v[154:155], v[16:17] op_sel:[0,1,0]
	v_pk_fma_f32 v[14:15], v[124:125], v[154:155], v[14:15] op_sel:[0,1,0]
	v_pk_fma_f32 v[78:79], v[80:81], v[130:131], v[78:79] op_sel_hi:[0,1,1]
	v_pk_fma_f32 v[72:73], v[80:81], v[132:133], v[72:73] op_sel_hi:[0,1,1]
	v_pk_fma_f32 v[58:59], v[84:85], v[130:131], v[58:59] op_sel_hi:[0,1,1]
	v_pk_fma_f32 v[56:57], v[84:85], v[132:133], v[56:57] op_sel_hi:[0,1,1]
	v_pk_fma_f32 v[42:43], v[126:127], v[130:131], v[42:43] op_sel_hi:[0,1,1]
	v_pk_fma_f32 v[40:41], v[126:127], v[132:133], v[40:41] op_sel_hi:[0,1,1]
	v_pk_fma_f32 v[26:27], v[152:153], v[130:131], v[26:27] op_sel_hi:[0,1,1]
	s_waitcnt vmcnt(0) lgkmcnt(0)
	v_pk_fma_f32 v[70:71], v[80:81], v[174:175], v[70:71] op_sel:[1,0,0]
	v_pk_fma_f32 v[68:69], v[80:81], v[176:177], v[68:69] op_sel:[1,0,0]
	v_pk_fma_f32 v[54:55], v[84:85], v[174:175], v[54:55] op_sel:[1,0,0]
	v_pk_fma_f32 v[52:53], v[84:85], v[176:177], v[52:53] op_sel:[1,0,0]
	v_pk_fma_f32 v[38:39], v[126:127], v[174:175], v[38:39] op_sel:[1,0,0]
	v_pk_fma_f32 v[36:37], v[126:127], v[176:177], v[36:37] op_sel:[1,0,0]
	v_pk_fma_f32 v[22:23], v[152:153], v[174:175], v[22:23] op_sel:[1,0,0]
	v_pk_fma_f32 v[20:21], v[152:153], v[176:177], v[20:21] op_sel:[1,0,0]
	v_pk_fma_f32 v[24:25], v[152:153], v[132:133], v[24:25] op_sel_hi:[0,1,1]
	v_pk_fma_f32 v[62:63], v[80:81], v[142:143], v[62:63] op_sel_hi:[0,1,1]
	v_pk_fma_f32 v[60:61], v[80:81], v[144:145], v[60:61] op_sel_hi:[0,1,1]
	v_pk_fma_f32 v[46:47], v[84:85], v[142:143], v[46:47] op_sel_hi:[0,1,1]
	v_pk_fma_f32 v[44:45], v[84:85], v[144:145], v[44:45] op_sel_hi:[0,1,1]
	v_pk_fma_f32 v[30:31], v[126:127], v[142:143], v[30:31] op_sel_hi:[0,1,1]
	v_pk_fma_f32 v[28:29], v[126:127], v[144:145], v[28:29] op_sel_hi:[0,1,1]
	v_pk_fma_f32 v[16:17], v[152:153], v[142:143], v[16:17] op_sel_hi:[0,1,1]
	v_pk_fma_f32 v[14:15], v[152:153], v[144:145], v[14:15] op_sel_hi:[0,1,1]
	v_pk_fma_f32 v[78:79], v[80:81], v[146:147], v[78:79] op_sel:[1,0,0]
	v_pk_fma_f32 v[72:73], v[80:81], v[148:149], v[72:73] op_sel:[1,0,0]
	v_pk_fma_f32 v[58:59], v[84:85], v[146:147], v[58:59] op_sel:[1,0,0]
	v_pk_fma_f32 v[56:57], v[84:85], v[148:149], v[56:57] op_sel:[1,0,0]
	v_pk_fma_f32 v[42:43], v[126:127], v[146:147], v[42:43] op_sel:[1,0,0]
	v_pk_fma_f32 v[40:41], v[126:127], v[148:149], v[40:41] op_sel:[1,0,0]
	v_pk_fma_f32 v[26:27], v[152:153], v[146:147], v[26:27] op_sel:[1,0,0]
	v_pk_fma_f32 v[24:25], v[152:153], v[148:149], v[24:25] op_sel:[1,0,0]
	s_waitcnt vmcnt(0) lgkmcnt(0)
	v_pk_fma_f32 v[66:67], v[80:81], v[178:179], v[66:67] op_sel:[1,0,0]
	v_pk_fma_f32 v[64:65], v[80:81], v[180:181], v[64:65] op_sel:[1,0,0]
	v_pk_fma_f32 v[50:51], v[84:85], v[178:179], v[50:51] op_sel:[1,0,0]
	v_pk_fma_f32 v[48:49], v[84:85], v[180:181], v[48:49] op_sel:[1,0,0]
	v_pk_fma_f32 v[34:35], v[126:127], v[178:179], v[34:35] op_sel:[1,0,0]
	v_pk_fma_f32 v[32:33], v[126:127], v[180:181], v[32:33] op_sel:[1,0,0]
	v_pk_fma_f32 v[18:19], v[152:153], v[178:179], v[18:19] op_sel:[1,0,0]
	v_pk_fma_f32 v[12:13], v[152:153], v[180:181], v[12:13] op_sel:[1,0,0]
	s_waitcnt vmcnt(0) lgkmcnt(0)
	v_pk_fma_f32 v[62:63], v[80:81], v[182:183], v[62:63] op_sel:[1,0,0]
	v_pk_fma_f32 v[60:61], v[80:81], v[184:185], v[60:61] op_sel:[1,0,0]
	v_pk_fma_f32 v[46:47], v[84:85], v[182:183], v[46:47] op_sel:[1,0,0]
	v_pk_fma_f32 v[44:45], v[84:85], v[184:185], v[44:45] op_sel:[1,0,0]
	v_pk_fma_f32 v[30:31], v[126:127], v[182:183], v[30:31] op_sel:[1,0,0]
	v_pk_fma_f32 v[28:29], v[126:127], v[184:185], v[28:29] op_sel:[1,0,0]
	v_pk_fma_f32 v[16:17], v[152:153], v[182:183], v[16:17] op_sel:[1,0,0]
	v_pk_fma_f32 v[14:15], v[152:153], v[184:185], v[14:15] op_sel:[1,0,0]
	s_cbranch_scc0 .LBB0_205
	s_ashr_i32 s43, s42, 31
	v_mov_b32_e32 v74, 0
	s_and_saveexec_b64 s[38:39], vcc
	s_cbranch_execz .LBB0_208
	s_lshl_b64 s[0:1], s[42:43], 7
	v_lshl_add_u64 v[74:75], v[0:1], 0, s[0:1]
	global_load_dword v74, v[74:75], off
